# preparation on 128 workgroups (was 171): 43 more workgroups stream the decode from the start
# baseline (speedup 1.0000x reference)
; __device__ __forceinline__ void p2_rwkv_prep(const Params& P, float* lds) {
;     const int tid = threadIdx.x, lane = tid & 63, wave = tid >> 6;
;     const bf16_t* prw = (const bf16_t*)(P.ws + WS_PRW);
;     float* RSB = (float*)(P.ws + WS_RSB);
;     constexpr int CT = 8, NCHK = NTK / CT;
;     float* xbuf = lds;
;     float* yt = lds + 2 * CT * 128 + wave * (2 * CT * 64);
;     float* ot = lds + 2 * CT * 128 + 8 * (2 * CT * 64) + wave * 768;
;     prep_bf16x8 wbh[2][4][2], wbl[2][4][2];
;     float w0c = 0.f, a0c = 0.f, kkc = 0.f, kac = 0.f, rkc = 0.f, mur = 0.f, muk = 0.f, muv = 0.f, mux = 0.f;
;     if (tid < RW) {
;         const prep_bf16x8* LF = (const prep_bf16x8*)(P.ws + WS_LFRAG);
; #pragma unroll
;         for (int mt = 0; mt < 2; ++mt)
; #pragma unroll
;             for (int nt = 0; nt < 4; ++nt)
; #pragma unroll
;                 for (int s = 0; s < 2; ++s) { const int fi = (((mt * 6 + wave) * 4 + nt) * 2 + s) * 64 + lane; wbh[mt][nt][s] = LF[fi]; wbl[mt][nt][s] = LF[2 * 6 * 4 * 2 * 64 + fi]; }
;         w0c = P.w0[tid]; a0c = P.a0[tid]; kkc = P.k_k[tid]; kac = P.k_a[tid]; rkc = P.r_k[tid];
;         mur = P.mu_shift[tid]; muk = P.mu_shift[RW + tid]; muv = P.mu_shift[2 * RW + tid];
;     } else {
; #pragma unroll
;         for (int mt = 0; mt < 2; ++mt)
; #pragma unroll
;             for (int nt = 0; nt < 4; ++nt)
; #pragma unroll
;                 for (int s = 0; s < 2; ++s)
; #pragma unroll
;                     for (int j = 0; j < 8; ++j) { wbh[mt][nt][s][j] = 0; wbl[mt][nt][s][j] = 0; }
;         mux = P.mu_shift[1152 + (tid - RW)];
;     }
;     int ch = blockIdx.x;
;     if (tid >= RW && ch < NCHK) prep_produce(P, prw, ch, xbuf, tid - RW, mux);
; __global__ void __launch_bounds__(512, 2) mk_fwd(Params P) {
;     ...
;     if (IN(2)) {
;         if (blockIdx.x < NPREP) {
;             p2_rwkv_prep(P, ldsf);
.LBB0_699:
	s_cmp_lt_i32 s60, 3
	s_cselect_b64 s[2:3], -1, 0
	s_and_b64 s[0:1], s[2:3], s[0:1]
	s_andn2_b64 vcc, exec, s[0:1]
	s_cbranch_vccnz .LBB0_939
	s_cmpk_gt_u32 s56, 0x7f
	s_cbranch_scc1 .LBB0_905
	s_movk_i32 s0, 0x180
	v_cmp_gt_u32_e64 s[4:5], s0, v0
	s_movk_i32 s0, 0x17f
	v_cmp_lt_u32_e32 vcc, s0, v0
	s_and_saveexec_b64 s[0:1], vcc
	s_xor_b64 s[0:1], exec, s[0:1]
	s_cbranch_execz .LBB0_703
	v_readlane_b32 s8, v252, 16
	v_lshlrev_b32_e32 v1, 2, v0
	v_readlane_b32 s18, v252, 26
	v_readlane_b32 s19, v252, 27
	v_readlane_b32 s9, v252, 17
	v_readlane_b32 s10, v252, 18
	v_readlane_b32 s11, v252, 19
	v_readlane_b32 s12, v252, 20
	v_readlane_b32 s13, v252, 21
	global_load_dword v173, v1, s[18:19] offset:3072
	v_readlane_b32 s14, v252, 22
	v_readlane_b32 s15, v252, 23
	v_readlane_b32 s16, v252, 24
	v_readlane_b32 s17, v252, 25
	v_readlane_b32 s20, v252, 28
	v_readlane_b32 s21, v252, 29
	v_readlane_b32 s22, v252, 30
	v_readlane_b32 s23, v252, 31

; __device__ __forceinline__ float bf2f(bf16_t b) { return __uint_as_float(((unsigned)b) << 16); }
; __device__ __forceinline__ void p2_rwkv_prep(const Params& P, float* lds) {
;     ...
;     int ch = blockIdx.x;
;     if (tid >= RW && ch < NCHK) prep_produce(P, prw, ch, xbuf, tid - RW, mux);
;     for (int it = 0; ch < NCHK; ch += NPREP, ++it) {
;         const int tok0 = ch * CT;
;         float* bufc = xbuf + (it & 1) * (CT * 128); float* bufn = xbuf + ((it + 1) & 1) * (CT * 128);
;         float nr[4], nk[4], nv[4], qr = 0.f, qk = 0.f, qv = 0.f;
;         if (tid < RW) {
; #pragma unroll
;             for (int q = 0; q < 4; ++q) { const bf16_t* p = prw + (size_t)(tok0 + q) * RCOLS + tid; nr[q] = bf2f(p[0]); nk[q] = bf2f(p[RW]); nv[q] = bf2f(p[2 * RW]); }
;             if (tok0 < NTOK && (tok0 & (SEQ - 1))) { const bf16_t* p = prw + (size_t)(tok0 - 1) * RCOLS + tid; qr = bf2f(p[0]); qk = bf2f(p[RW]); qv = bf2f(p[2 * RW]); }
;         }
.LBB0_760:
	s_or_b64 exec, exec, s[2:3]
	v_lshl_add_u32 v130, v170, 12, 0
	v_lshlrev_b32_e32 v132, 1, v0
	v_mov_b32_e32 v133, 0
	v_lshlrev_b32_e32 v134, 9, v0
	v_lshlrev_b32_e32 v172, 2, v1
	v_lshlrev_b32_e32 v131, 10, v170
	v_lshl_add_u64 v[176:177], s[0:1], 0, v[132:133]
	v_and_b32_e32 v134, 0xe00, v134
	v_and_b32_e32 v132, 0x60, v132
	v_add_u32_e32 v199, v130, v172
	s_load_dwordx16 s[36:51], s[58:59], 0x0
	v_add3_u32 v198, 0, v134, v132
	v_and_b32_e32 v132, 8, v0
	v_sub_u32_e32 v200, v199, v131
	v_cmp_eq_u32_e64 s[8:9], 0, v132
	v_and_b32_e32 v132, 15, v0
	v_mad_u32_u24 v131, v1, 12, v200
	s_add_u32 s18, s78, 0xa2d4000
	v_lshl_add_u32 v134, v132, 2, v130
	v_lshlrev_b32_e32 v130, 6, v0
	v_mad_i32_i24 v203, v1, -12, v131
	s_addc_u32 s19, s79, 0
	v_cmp_gt_u32_e64 s[10:11], 32, v1
	v_cmp_eq_u32_e64 s[12:13], 0, v1
	v_and_b32_e32 v130, 0x400, v130
	v_mad_u32_u24 v1, v1, 12, v203
	v_lshlrev_b32_e32 v132, 2, v0
	v_lshl_add_u64 v[180:181], v[174:175], 1, s[0:1]
	s_lshl_b32 s0, s56, 3
	v_mov_b32_e32 v171, v133
	v_cmp_gt_u32_e64 s[14:15], 64, v174
	s_movk_i32 s22, 0x400
	v_add_u32_e32 v201, 0xa000, v131
	v_add_u32_e32 v202, 0xa400, v131
	v_add_u32_e32 v204, 0xa600, v1
	v_add_u32_e32 v205, 0xaa00, v1
	v_lshl_add_u32 v206, v174, 2, 0
	s_waitcnt lgkmcnt(0)
	v_lshl_add_u64 v[178:179], s[50:51], 0, v[132:133]
	s_add_i32 s23, s0, 0x407
	s_mov_b32 s24, 0x3fb8aa3b
	s_movk_i32 s25, 0x610
	s_mov_b32 s26, 0x3f200000
	s_mov_b32 s27, 0xc2ce8ed0
	s_mov_b32 s28, 0x42b17218
	v_mov_b32_e32 v207, 0x3ca908c9
	s_brev_b32 s29, -2
	v_mov_b32_e32 v208, 0xa00
	v_add_u32_e32 v209, v134, v130
	v_mov_b32_e32 v210, 0x1400
	v_mov_b32_e32 v211, 0x610
	v_mov_b32_e32 v212, 0x7f800000
	s_mov_b32 s30, s56
	s_branch .LBB0_764

; __device__ __forceinline__ float bf2f(bf16_t b) { return __uint_as_float(((unsigned)b) << 16); }
; __device__ __forceinline__ void p2_rwkv_prep(const Params& P, float* lds) {
;     ...
;     for (int it = 0; ch < NCHK; ch += NPREP, ++it) {
;         const int tok0 = ch * CT;
;         float* bufc = xbuf + (it & 1) * (CT * 128); float* bufn = xbuf + ((it + 1) & 1) * (CT * 128);
;         float nr[4], nk[4], nv[4], qr = 0.f, qk = 0.f, qv = 0.f;
;         if (tid < RW) {
; #pragma unroll
;             for (int q = 0; q < 4; ++q) { const bf16_t* p = prw + (size_t)(tok0 + q) * RCOLS + tid; nr[q] = bf2f(p[0]); nk[q] = bf2f(p[RW]); nv[q] = bf2f(p[2 * RW]); }
;             if (tok0 < NTOK && (tok0 & (SEQ - 1))) { const bf16_t* p = prw + (size_t)(tok0 - 1) * RCOLS + tid; qr = bf2f(p[0]); qk = bf2f(p[RW]); qv = bf2f(p[2 * RW]); }
;         }
.LBB0_763:
	s_or_b64 exec, exec, s[0:1]
	s_add_i32 s0, s30, 0x80
	s_addk_i32 s23, 0x400
	s_addk_i32 s22, 0x400
	s_cmpk_lt_i32 s30, 0x784
	s_mov_b32 s30, s0
	s_cbranch_scc0 .LBB0_901
.LBB0_764:
	s_cmpk_gt_i32 s30, 0x7ff
	s_cselect_b64 s[98:99], -1, 0
	v_mov_b32_e32 v255, 1.0
	s_add_i32 s31, s23, 0xfffffbf9
	v_mov_b32_e32 v131, 0
	v_mov_b32_e32 v130, 0
	v_mov_b32_e32 v1, 0
	s_and_saveexec_b64 s[0:1], s[4:5]
	s_cbranch_execz .LBB0_768
	v_mad_u64_u32 v[130:131], s[2:3], s31, v208, v[176:177]
	s_add_i32 s2, s23, 0xfffffbfa
	s_nop 0
	v_mad_u64_u32 v[134:135], s[2:3], s2, v208, v[176:177]
	s_add_i32 s2, s23, 0xfffffbfb
	s_nop 0
	v_mad_u64_u32 v[146:147], s[2:3], s2, v208, v[176:177]
	global_load_ushort v141, v[130:131], off
	global_load_ushort v144, v[130:131], off offset:768
	global_load_ushort v139, v[134:135], off
	global_load_ushort v142, v[134:135], off offset:768
	s_nop 0
	global_load_ushort v135, v[134:135], off offset:1536
	s_nop 0
	global_load_ushort v134, v[146:147], off
	global_load_ushort v138, v[146:147], off offset:768
	global_load_ushort v143, v[130:131], off offset:1536
	s_add_i32 s2, s23, 0xfffffbfc
	v_mad_u64_u32 v[130:131], s[2:3], s2, v208, v[176:177]
	global_load_ushort v136, v[130:131], off
	global_load_ushort v140, v[130:131], off offset:768
	global_load_ushort v132, v[130:131], off offset:1536
	global_load_ushort v137, v[146:147], off offset:1536
	s_cmpk_gt_i32 s30, 0x7ff
	s_cselect_b64 s[2:3], -1, 0
	s_and_b32 s16, s30, 0x1ff
	s_cmp_eq_u32 s16, 0
	s_cselect_b64 s[16:17], -1, 0
	s_or_b64 s[2:3], s[2:3], s[16:17]
	v_mov_b32_e32 v1, 0
	s_and_b64 vcc, exec, s[2:3]
	v_mov_b32_e32 v130, 0
	v_mov_b32_e32 v131, 0
	s_cbranch_vccnz .LBB0_767
	s_add_i32 s2, s23, 0xfffffbf8
	v_mad_i64_i32 v[130:131], s[2:3], s2, v208, v[176:177]
	global_load_ushort v1, v[130:131], off
	global_load_ushort v145, v[130:131], off offset:1536
	global_load_ushort v146, v[130:131], off offset:768
	s_waitcnt vmcnt(0)
	v_lshlrev_b32_e32 v131, 16, v1
	v_lshlrev_b32_e32 v130, 16, v145
	v_lshlrev_b32_e32 v1, 16, v146

; __device__ __forceinline__ float bf2f(bf16_t b) { return __uint_as_float(((unsigned)b) << 16); }
; __device__ __forceinline__ float sigmoidf_(float x) { return 1.f / (1.f + __expf(-x)); }
; __device__ __forceinline__ void p2_rwkv_prep(const Params& P, float* lds) {
;     ...
;             for (int tk = tg; tk < tg + 4; ++tk) {
;                 const int tok = tok0 + tk;
;                 if (tok >= NTOK) { const float* p = P.state_shift + (size_t)(tok - NTOK) * RCOLS + tid; qr = p[0]; qk = p[RW]; qv = p[2 * RW]; }
;                 const float cr = nr[tk & 3], ck = nk[tk & 3], cv = nv[tk & 3];
;                 if (tk + 4 < CT) { const bf16_t* p = prw + (size_t)(tok + 4) * RCOLS + tid; nr[tk & 3] = bf2f(p[0]); nk[tk & 3] = bf2f(p[RW]); nv[tk & 3] = bf2f(p[2 * RW]); }
;                 const float r = cr + (qr - cr) * mur, kraw = ck + (qk - ck) * muk, v = cv + (qv - cv) * muv;
;                 qr = cr; qk = ck; qv = cv;
;                 const float aw = w0c + yt[tk * 64 + cc], aa = a0c + yt[(CT + tk) * 64 + cc];
;                 const float w = __expf(-DECAY_SCALE * sigmoidf_(aw)), a = sigmoidf_(aa);
;                 const float kkv = kraw * kkc;
;                 const float n2 = wave_sum_fast(kkv * kkv);
;                 const float kk = kkv * rsqrtf(fmaxf(n2, 1e-12f));
;                 const float kmod = kraw * (1.f + (a - 1.f) * kac);
;                 const float bb = kk * a;
;                 const float br = wave_sum_fast(bb * r);
;                 ekk[tk - tg] = kk; ew[tk - tg] = w; ebb[tk - tg] = bb; ekm[tk - tg] = kmod; ewr[tk - tg] = w * r - kk * br; ev[tk - tg] = v;
;                 ebr[tk - tg] = br; ekr[tk - tg] = wave_sum_fast(kmod * r); erk[tk - tg] = wave_sum_fast(r * kmod * rkc);
.LBB0_785:
	s_or_b64 exec, exec, s[2:3]
	s_waitcnt lgkmcnt(0)
	s_cmpk_gt_i32 s30, 0x7ff
	s_cselect_b64 s[2:3], -1, 0
	s_cmpk_lt_i32 s30, 0x800
	s_cbranch_scc1 .LBB0_787
	s_add_i32 s16, s23, 0xffffbbf9
	v_mad_u64_u32 v[134:135], s[16:17], s16, v210, v[178:179]
	global_load_dword v131, v[134:135], off
	global_load_dword v1, v[134:135], off offset:1536
	global_load_dword v130, v[134:135], off offset:3072
.LBB0_787:
	s_add_i32 s16, s23, 0xfffffbfd
	v_mad_u64_u32 v[136:137], s[20:21], s16, v208, v[176:177]
	ds_read2st64_b32 v[134:135], v199 offset0:32 offset1:40
	global_load_ushort v156, v[136:137], off
	global_load_ushort v158, v[136:137], off offset:768
	global_load_ushort v157, v[136:137], off offset:1536
	s_waitcnt vmcnt(5)
	v_sub_f32_e32 v131, v131, v188
	v_fma_f32 v152, v196, v131, v188
	s_waitcnt vmcnt(4)
	v_sub_f32_e32 v1, v1, v189
	s_waitcnt lgkmcnt(0)
	v_add_f32_e32 v132, v194, v135
	v_mul_f32_e32 v132, 0xbfb8aa3b, v132
	v_exp_f32_e32 v132, v132
	v_mov_b32_e32 v136, v189
	v_fmac_f32_e32 v136, v195, v1
	v_mov_b32_e32 v167, v213
	v_add_f32_e32 v131, 1.0, v132
	v_div_scale_f32 v132, s[20:21], v131, v131, 1.0
	v_rcp_f32_e32 v135, v132
	s_nop 0
	v_fma_f32 v1, -v132, v135, 1.0
	v_fmac_f32_e32 v135, v1, v135
	v_div_scale_f32 v1, vcc, 1.0, v131, 1.0
	v_mul_f32_e32 v137, v1, v135
	v_fma_f32 v138, -v132, v137, v1
	v_fmac_f32_e32 v137, v138, v135
	v_fma_f32 v1, -v132, v137, v1
	v_mul_f32_e32 v132, v193, v136
	v_mul_f32_e32 v138, v132, v132
	v_div_fmas_f32 v1, v1, v135, v137
	v_div_fixup_f32 v1, v1, v131, 1.0
	v_mov_b32_dpp v138, v138 quad_perm:[1,0,3,2] row_mask:0xf bank_mask:0xf bound_ctrl:1
	v_fmac_f32_e32 v138, v132, v132
	v_add_f32_e32 v131, -1.0, v1
	v_fma_f32 v131, v192, v131, 1.0
	v_add_f32_dpp v138, v138, v138 quad_perm:[2,3,0,1] row_mask:0xf bank_mask:0xf bound_ctrl:1
	v_mul_f32_e32 v154, v136, v131
	s_andn2_b64 vcc, exec, s[2:3]
	v_add_f32_dpp v138, v138, v138 row_ror:4 row_mask:0xf bank_mask:0xf bound_ctrl:1
	s_nop 1
	v_add_f32_dpp v138, v138, v138 row_ror:8 row_mask:0xf bank_mask:0xf bound_ctrl:1
	v_mov_b32_e32 v139, v138
	s_nop 1
	v_permlane16_swap_b32_e32 v138, v139
	v_add_f32_e32 v138, v138, v139
	v_mov_b32_e32 v139, v138
	s_nop 1
	v_permlane32_swap_b32_e32 v138, v139
	v_add_f32_e32 v138, v138, v139
	v_max_f32_e32 v138, 0x2b8cbccc, v138
	v_rsq_f32_e32 v138, v138
	s_nop 0
	v_mul_f32_e32 v132, v132, v138
	v_mul_f32_e32 v155, v1, v132
	v_mul_f32_e32 v1, v152, v155
	s_nop 1
	v_mov_b32_dpp v1, v1 quad_perm:[1,0,3,2] row_mask:0xf bank_mask:0xf bound_ctrl:1
	v_fmac_f32_e32 v1, v152, v155
	s_nop 1
	v_add_f32_dpp v1, v1, v1 quad_perm:[2,3,0,1] row_mask:0xf bank_mask:0xf bound_ctrl:1
	s_nop 1
	v_add_f32_dpp v1, v1, v1 row_ror:4 row_mask:0xf bank_mask:0xf bound_ctrl:1
	s_nop 1
	v_add_f32_dpp v1, v1, v1 row_ror:8 row_mask:0xf bank_mask:0xf bound_ctrl:1
	v_mov_b32_e32 v131, v1
	s_nop 1
	v_permlane16_swap_b32_e32 v1, v131
	v_add_f32_e32 v136, v1, v131
	v_mul_f32_e32 v1, v152, v154
	v_mov_b32_e32 v150, v136
	s_nop 1
	v_permlane32_swap_b32_e32 v136, v150
	v_mov_b32_dpp v131, v1 quad_perm:[1,0,3,2] row_mask:0xf bank_mask:0xf bound_ctrl:1
	v_fmac_f32_e32 v131, v152, v154
	s_nop 1
	v_add_f32_dpp v131, v131, v131 quad_perm:[2,3,0,1] row_mask:0xf bank_mask:0xf bound_ctrl:1
	s_nop 1
	v_add_f32_dpp v131, v131, v131 row_ror:4 row_mask:0xf bank_mask:0xf bound_ctrl:1
	s_nop 1
	v_add_f32_dpp v131, v131, v131 row_ror:8 row_mask:0xf bank_mask:0xf bound_ctrl:1
	v_mov_b32_e32 v135, v131
	s_nop 1
	v_permlane16_swap_b32_e32 v131, v135
	v_add_f32_e32 v137, v131, v135
	v_mul_f32_e32 v131, v197, v1
	v_mov_b32_e32 v151, v137
	s_nop 1
	v_permlane32_swap_b32_e32 v137, v151
	v_mov_b32_dpp v131, v131 quad_perm:[1,0,3,2] row_mask:0xf bank_mask:0xf bound_ctrl:1
	v_fmac_f32_e32 v131, v197, v1
	s_nop 1
	v_add_f32_dpp v1, v131, v131 quad_perm:[2,3,0,1] row_mask:0xf bank_mask:0xf bound_ctrl:1
	s_nop 1
	v_add_f32_dpp v1, v1, v1 row_ror:4 row_mask:0xf bank_mask:0xf bound_ctrl:1
	s_nop 1
	v_add_f32_dpp v1, v1, v1 row_ror:8 row_mask:0xf bank_mask:0xf bound_ctrl:1
	v_mov_b32_e32 v131, v1
	s_nop 1
	v_permlane16_swap_b32_e32 v1, v131
	v_add_f32_e32 v168, v1, v131
	v_mov_b32_e32 v169, v168
	s_nop 1
	v_permlane32_swap_b32_e32 v168, v169
	s_cbranch_vccnz .LBB0_789
	s_add_i32 s2, s23, 0xffffbbfa
	v_mad_u64_u32 v[138:139], s[2:3], s2, v210, v[178:179]
	global_load_dword v188, v[138:139], off
	global_load_dword v189, v[138:139], off offset:1536
	global_load_dword v167, v[138:139], off offset:3072
; __device__ __forceinline__ float bf2f(bf16_t b) { return __uint_as_float(((unsigned)b) << 16); }
; __device__ __forceinline__ float sigmoidf_(float x) { return 1.f / (1.f + __expf(-x)); }
; __device__ __forceinline__ void p2_rwkv_prep(const Params& P, float* lds) {
;     ...
;             for (int tk = tg; tk < tg + 4; ++tk) {
;                 const int tok = tok0 + tk;
;                 if (tok >= NTOK) { const float* p = P.state_shift + (size_t)(tok - NTOK) * RCOLS + tid; qr = p[0]; qk = p[RW]; qv = p[2 * RW]; }
;                 const float cr = nr[tk & 3], ck = nk[tk & 3], cv = nv[tk & 3];
;                 if (tk + 4 < CT) { const bf16_t* p = prw + (size_t)(tok + 4) * RCOLS + tid; nr[tk & 3] = bf2f(p[0]); nk[tk & 3] = bf2f(p[RW]); nv[tk & 3] = bf2f(p[2 * RW]); }
;                 const float r = cr + (qr - cr) * mur, kraw = ck + (qk - ck) * muk, v = cv + (qv - cv) * muv;
;                 qr = cr; qk = ck; qv = cv;
;                 const float aw = w0c + yt[tk * 64 + cc], aa = a0c + yt[(CT + tk) * 64 + cc];
;                 const float w = __expf(-DECAY_SCALE * sigmoidf_(aw)), a = sigmoidf_(aa);
;                 const float kkv = kraw * kkc;
;                 const float n2 = wave_sum_fast(kkv * kkv);
;                 const float kk = kkv * rsqrtf(fmaxf(n2, 1e-12f));
;                 const float kmod = kraw * (1.f + (a - 1.f) * kac);
;                 const float bb = kk * a;
;                 const float br = wave_sum_fast(bb * r);
;                 ekk[tk - tg] = kk; ew[tk - tg] = w; ebb[tk - tg] = bb; ekm[tk - tg] = kmod; ewr[tk - tg] = w * r - kk * br; ev[tk - tg] = v;
;                 ebr[tk - tg] = br; ekr[tk - tg] = wave_sum_fast(kmod * r); erk[tk - tg] = wave_sum_fast(r * kmod * rkc);
.LBB0_789:
	s_add_i32 s17, s23, 0xfffffbfe
	v_mad_u64_u32 v[140:141], s[2:3], s17, v208, v[176:177]
	ds_read2st64_b32 v[138:139], v199 offset0:33 offset1:41
	global_load_ushort v159, v[140:141], off
	global_load_ushort v161, v[140:141], off offset:768
	global_load_ushort v160, v[140:141], off offset:1536
	s_waitcnt vmcnt(5)
	v_sub_f32_e32 v131, v188, v186
	s_waitcnt vmcnt(4)
	v_sub_f32_e32 v140, v189, v187
	v_mov_b32_e32 v141, v187
	s_waitcnt lgkmcnt(0)
	v_add_f32_e32 v1, v194, v139
	v_mul_f32_e32 v1, 0xbfb8aa3b, v1
	v_exp_f32_e32 v1, v1
	v_fma_f32 v139, v196, v131, v186
	v_fmac_f32_e32 v141, v195, v140
	s_add_i32 s33, s23, 0xfffffbfb
	v_add_f32_e32 v1, 1.0, v1
	v_div_scale_f32 v131, s[2:3], v1, v1, 1.0
	v_rcp_f32_e32 v135, v131
	s_cmpk_lt_i32 s33, 0x4000
	v_mov_b32_e32 v218, v214
	v_fma_f32 v140, -v131, v135, 1.0
	v_fmac_f32_e32 v135, v140, v135
	v_div_scale_f32 v140, vcc, 1.0, v1, 1.0
	v_mul_f32_e32 v142, v140, v135
	v_fma_f32 v143, -v131, v142, v140
	v_fmac_f32_e32 v142, v143, v135
	v_fma_f32 v131, -v131, v142, v140
	v_mul_f32_e32 v140, v193, v141
	v_mul_f32_e32 v143, v140, v140
	v_div_fmas_f32 v131, v131, v135, v142
	v_div_fixup_f32 v1, v131, v1, 1.0
	v_mov_b32_dpp v143, v143 quad_perm:[1,0,3,2] row_mask:0xf bank_mask:0xf bound_ctrl:1
	v_fmac_f32_e32 v143, v140, v140
	v_add_f32_e32 v131, -1.0, v1
	v_fma_f32 v131, v192, v131, 1.0
	v_add_f32_dpp v143, v143, v143 quad_perm:[2,3,0,1] row_mask:0xf bank_mask:0xf bound_ctrl:1
	v_mul_f32_e32 v189, v141, v131
	s_nop 0
	v_add_f32_dpp v143, v143, v143 row_ror:4 row_mask:0xf bank_mask:0xf bound_ctrl:1
	s_nop 1
	v_add_f32_dpp v143, v143, v143 row_ror:8 row_mask:0xf bank_mask:0xf bound_ctrl:1
	v_mov_b32_e32 v144, v143
	s_nop 1
	v_permlane16_swap_b32_e32 v143, v144
	v_add_f32_e32 v143, v143, v144
	v_mov_b32_e32 v144, v143
	s_nop 1
	v_permlane32_swap_b32_e32 v143, v144
	v_add_f32_e32 v143, v143, v144
	v_max_f32_e32 v143, 0x2b8cbccc, v143
	v_rsq_f32_e32 v143, v143
	s_nop 0
	v_mul_f32_e32 v188, v140, v143
	v_mul_f32_e32 v217, v1, v188
	v_mul_f32_e32 v1, v139, v217
	s_nop 1
	v_mov_b32_dpp v1, v1 quad_perm:[1,0,3,2] row_mask:0xf bank_mask:0xf bound_ctrl:1
	v_fmac_f32_e32 v1, v139, v217
	s_nop 1
	v_add_f32_dpp v1, v1, v1 quad_perm:[2,3,0,1] row_mask:0xf bank_mask:0xf bound_ctrl:1
	s_nop 1
	v_add_f32_dpp v1, v1, v1 row_ror:4 row_mask:0xf bank_mask:0xf bound_ctrl:1
	s_nop 1
	v_add_f32_dpp v1, v1, v1 row_ror:8 row_mask:0xf bank_mask:0xf bound_ctrl:1
	v_mov_b32_e32 v131, v1
	s_nop 1
	v_permlane16_swap_b32_e32 v1, v131
	v_add_f32_e32 v142, v1, v131
	v_mul_f32_e32 v1, v139, v189
	v_mov_b32_e32 v144, v142
	s_nop 1
	v_permlane32_swap_b32_e32 v142, v144
	v_mov_b32_dpp v131, v1 quad_perm:[1,0,3,2] row_mask:0xf bank_mask:0xf bound_ctrl:1
	v_fmac_f32_e32 v131, v139, v189
	s_nop 1
	v_add_f32_dpp v131, v131, v131 quad_perm:[2,3,0,1] row_mask:0xf bank_mask:0xf bound_ctrl:1
	s_nop 1
	v_add_f32_dpp v131, v131, v131 row_ror:4 row_mask:0xf bank_mask:0xf bound_ctrl:1
	s_nop 1
	v_add_f32_dpp v131, v131, v131 row_ror:8 row_mask:0xf bank_mask:0xf bound_ctrl:1
	v_mov_b32_e32 v135, v131
	s_nop 1
	v_permlane16_swap_b32_e32 v131, v135
	v_add_f32_e32 v143, v131, v135
	v_mul_f32_e32 v131, v197, v1
	v_mov_b32_e32 v145, v143
	s_nop 1
	v_permlane32_swap_b32_e32 v143, v145
	v_mov_b32_dpp v131, v131 quad_perm:[1,0,3,2] row_mask:0xf bank_mask:0xf bound_ctrl:1
	v_fmac_f32_e32 v131, v197, v1
	s_nop 1
	v_add_f32_dpp v1, v131, v131 quad_perm:[2,3,0,1] row_mask:0xf bank_mask:0xf bound_ctrl:1
	s_nop 1
	v_add_f32_dpp v1, v1, v1 row_ror:4 row_mask:0xf bank_mask:0xf bound_ctrl:1
	s_nop 1
	v_add_f32_dpp v1, v1, v1 row_ror:8 row_mask:0xf bank_mask:0xf bound_ctrl:1
	v_mov_b32_e32 v131, v1
	s_nop 1
	v_permlane16_swap_b32_e32 v1, v131
	v_add_f32_e32 v219, v1, v131
	v_mov_b32_e32 v220, v219
	s_nop 1
	v_permlane32_swap_b32_e32 v219, v220
	s_cbranch_scc1 .LBB0_791
	s_add_i32 s2, s23, 0xffffbbfb
	v_mad_u64_u32 v[140:141], s[2:3], s2, v210, v[178:179]
	global_load_dword v186, v[140:141], off
	global_load_dword v187, v[140:141], off offset:1536
	global_load_dword v218, v[140:141], off offset:3072
.LBB0_791:
	s_add_i32 s20, s23, 0xfffffbff
	v_mad_u64_u32 v[146:147], s[2:3], s20, v208, v[176:177]
	ds_read2st64_b32 v[140:141], v199 offset0:34 offset1:42
	global_load_ushort v162, v[146:147], off
	global_load_ushort v164, v[146:147], off offset:768
	global_load_ushort v163, v[146:147], off offset:1536
	s_waitcnt vmcnt(5)
	v_sub_f32_e32 v131, v186, v184
	s_waitcnt vmcnt(4)
	v_sub_f32_e32 v146, v187, v185
	v_mov_b32_e32 v147, v185
	s_waitcnt lgkmcnt(0)
; __device__ __forceinline__ float bf2f(bf16_t b) { return __uint_as_float(((unsigned)b) << 16); }
; __device__ __forceinline__ float sigmoidf_(float x) { return 1.f / (1.f + __expf(-x)); }
; __device__ __forceinline__ void p2_rwkv_prep(const Params& P, float* lds) {
;     ...
;             for (int tk = tg; tk < tg + 4; ++tk) {
;                 const int tok = tok0 + tk;
;                 if (tok >= NTOK) { const float* p = P.state_shift + (size_t)(tok - NTOK) * RCOLS + tid; qr = p[0]; qk = p[RW]; qv = p[2 * RW]; }
;                 const float cr = nr[tk & 3], ck = nk[tk & 3], cv = nv[tk & 3];
;                 if (tk + 4 < CT) { const bf16_t* p = prw + (size_t)(tok + 4) * RCOLS + tid; nr[tk & 3] = bf2f(p[0]); nk[tk & 3] = bf2f(p[RW]); nv[tk & 3] = bf2f(p[2 * RW]); }
;                 const float r = cr + (qr - cr) * mur, kraw = ck + (qk - ck) * muk, v = cv + (qv - cv) * muv;
;                 qr = cr; qk = ck; qv = cv;
;                 const float aw = w0c + yt[tk * 64 + cc], aa = a0c + yt[(CT + tk) * 64 + cc];
;                 const float w = __expf(-DECAY_SCALE * sigmoidf_(aw)), a = sigmoidf_(aa);
;                 const float kkv = kraw * kkc;
;                 const float n2 = wave_sum_fast(kkv * kkv);
;                 const float kk = kkv * rsqrtf(fmaxf(n2, 1e-12f));
;                 const float kmod = kraw * (1.f + (a - 1.f) * kac);
;                 const float bb = kk * a;
;                 const float br = wave_sum_fast(bb * r);
;                 ekk[tk - tg] = kk; ew[tk - tg] = w; ebb[tk - tg] = bb; ekm[tk - tg] = kmod; ewr[tk - tg] = w * r - kk * br; ev[tk - tg] = v;
;                 ebr[tk - tg] = br; ekr[tk - tg] = wave_sum_fast(kmod * r); erk[tk - tg] = wave_sum_fast(r * kmod * rkc);
	v_add_f32_e32 v1, v194, v141
	v_mul_f32_e32 v1, 0xbfb8aa3b, v1
	v_exp_f32_e32 v1, v1
	v_fma_f32 v141, v196, v131, v184
	v_fmac_f32_e32 v147, v195, v146
	s_add_i32 s34, s23, 0xfffffbfc
	v_add_f32_e32 v1, 1.0, v1
	v_div_scale_f32 v131, s[2:3], v1, v1, 1.0
	v_rcp_f32_e32 v135, v131
	s_cmpk_lt_i32 s34, 0x4000
	v_mov_b32_e32 v222, v216
	v_fma_f32 v146, -v131, v135, 1.0
	v_fmac_f32_e32 v135, v146, v135
	v_div_scale_f32 v146, vcc, 1.0, v1, 1.0
	v_mul_f32_e32 v148, v146, v135
	v_fma_f32 v149, -v131, v148, v146
	v_fmac_f32_e32 v148, v149, v135
	v_fma_f32 v131, -v131, v148, v146
	v_mul_f32_e32 v146, v193, v147
	v_mul_f32_e32 v149, v146, v146
	v_div_fmas_f32 v131, v131, v135, v148
	v_div_fixup_f32 v1, v131, v1, 1.0
	v_mov_b32_dpp v149, v149 quad_perm:[1,0,3,2] row_mask:0xf bank_mask:0xf bound_ctrl:1
	v_fmac_f32_e32 v149, v146, v146
	v_add_f32_e32 v131, -1.0, v1
	v_fma_f32 v131, v192, v131, 1.0
	v_add_f32_dpp v149, v149, v149 quad_perm:[2,3,0,1] row_mask:0xf bank_mask:0xf bound_ctrl:1
	v_mul_f32_e32 v187, v147, v131
	s_nop 0
	v_add_f32_dpp v149, v149, v149 row_ror:4 row_mask:0xf bank_mask:0xf bound_ctrl:1
	s_nop 1
	v_add_f32_dpp v149, v149, v149 row_ror:8 row_mask:0xf bank_mask:0xf bound_ctrl:1
	v_mov_b32_e32 v153, v149
	s_nop 1
	v_permlane16_swap_b32_e32 v149, v153
	v_add_f32_e32 v149, v149, v153
	v_mov_b32_e32 v153, v149
	s_nop 1
	v_permlane32_swap_b32_e32 v149, v153
	v_add_f32_e32 v149, v149, v153
	v_max_f32_e32 v149, 0x2b8cbccc, v149
	v_rsq_f32_e32 v149, v149
	s_nop 0
	v_mul_f32_e32 v186, v146, v149
	v_mul_f32_e32 v221, v1, v186
	v_mul_f32_e32 v1, v141, v221
	s_nop 1
	v_mov_b32_dpp v1, v1 quad_perm:[1,0,3,2] row_mask:0xf bank_mask:0xf bound_ctrl:1
	v_fmac_f32_e32 v1, v141, v221
	s_nop 1
	v_add_f32_dpp v1, v1, v1 quad_perm:[2,3,0,1] row_mask:0xf bank_mask:0xf bound_ctrl:1
	s_nop 1
	v_add_f32_dpp v1, v1, v1 row_ror:4 row_mask:0xf bank_mask:0xf bound_ctrl:1
	s_nop 1
	v_add_f32_dpp v1, v1, v1 row_ror:8 row_mask:0xf bank_mask:0xf bound_ctrl:1
	v_mov_b32_e32 v131, v1
	s_nop 1
	v_permlane16_swap_b32_e32 v1, v131
	v_add_f32_e32 v146, v1, v131
	v_mul_f32_e32 v1, v141, v187
	v_mov_b32_e32 v148, v146
	s_nop 1
	v_permlane32_swap_b32_e32 v146, v148
	v_mov_b32_dpp v131, v1 quad_perm:[1,0,3,2] row_mask:0xf bank_mask:0xf bound_ctrl:1
	v_fmac_f32_e32 v131, v141, v187
	s_nop 1
	v_add_f32_dpp v131, v131, v131 quad_perm:[2,3,0,1] row_mask:0xf bank_mask:0xf bound_ctrl:1
	s_nop 1
	v_add_f32_dpp v131, v131, v131 row_ror:4 row_mask:0xf bank_mask:0xf bound_ctrl:1
	s_nop 1
	v_add_f32_dpp v131, v131, v131 row_ror:8 row_mask:0xf bank_mask:0xf bound_ctrl:1
	v_mov_b32_e32 v135, v131
	s_nop 1
	v_permlane16_swap_b32_e32 v131, v135
	v_add_f32_e32 v147, v131, v135
	v_mul_f32_e32 v131, v197, v1
	v_mov_b32_e32 v149, v147
	s_nop 1
	v_permlane32_swap_b32_e32 v147, v149
	v_mov_b32_dpp v131, v131 quad_perm:[1,0,3,2] row_mask:0xf bank_mask:0xf bound_ctrl:1
	v_fmac_f32_e32 v131, v197, v1
	s_nop 1
	v_add_f32_dpp v1, v131, v131 quad_perm:[2,3,0,1] row_mask:0xf bank_mask:0xf bound_ctrl:1
	s_nop 1
	v_add_f32_dpp v1, v1, v1 row_ror:4 row_mask:0xf bank_mask:0xf bound_ctrl:1
	s_nop 1
	v_add_f32_dpp v1, v1, v1 row_ror:8 row_mask:0xf bank_mask:0xf bound_ctrl:1
	v_mov_b32_e32 v131, v1
	s_nop 1
	v_permlane16_swap_b32_e32 v1, v131
	v_add_f32_e32 v223, v1, v131
	v_mov_b32_e32 v224, v223
	s_nop 1
	v_permlane32_swap_b32_e32 v223, v224
	s_cbranch_scc1 .LBB0_793
	s_add_i32 s2, s23, 0xffffbbfc
	v_mad_u64_u32 v[226:227], s[2:3], s2, v210, v[178:179]
	global_load_dword v184, v[226:227], off
	global_load_dword v185, v[226:227], off offset:1536
	global_load_dword v222, v[226:227], off offset:3072
; __device__ __forceinline__ float sigmoidf_(float x) { return 1.f / (1.f + __expf(-x)); }
; __device__ __forceinline__ void p2_rwkv_prep(const Params& P, float* lds) {
;     ...
;                 const float r = cr + (qr - cr) * mur, kraw = ck + (qk - ck) * muk, v = cv + (qv - cv) * muv;
;                 qr = cr; qk = ck; qv = cv;
;                 const float aw = w0c + yt[tk * 64 + cc], aa = a0c + yt[(CT + tk) * 64 + cc];
;                 const float w = __expf(-DECAY_SCALE * sigmoidf_(aw)), a = sigmoidf_(aa);
;                 const float kkv = kraw * kkc;
;                 const float n2 = wave_sum_fast(kkv * kkv);
;                 const float kk = kkv * rsqrtf(fmaxf(n2, 1e-12f));
;                 const float kmod = kraw * (1.f + (a - 1.f) * kac);
;                 const float bb = kk * a;
;                 const float br = wave_sum_fast(bb * r);
;                 ekk[tk - tg] = kk; ew[tk - tg] = w; ebb[tk - tg] = bb; ekm[tk - tg] = kmod; ewr[tk - tg] = w * r - kk * br; ev[tk - tg] = v;
;                 ebr[tk - tg] = br; ekr[tk - tg] = wave_sum_fast(kmod * r); erk[tk - tg] = wave_sum_fast(r * kmod * rkc);
;             }
; #pragma unroll
;             for (int tk = tg; tk < tg + 4; ++tk) {
;                 float* blk = RSB + ((size_t)(tok0 + tk) * RH + h) * RSB_BLK;
;                 float* oq = ot + (tk & 1) * 384;
;                 oq[cc] = ekk[tk - tg]; oq[64 + cc] = ew[tk - tg]; oq[128 + cc] = ebb[tk - tg]; oq[192 + cc] = ekm[tk - tg]; oq[256 + cc] = ewr[tk - tg]; oq[320 + cc] = ev[tk - tg];
;                 __builtin_amdgcn_wave_barrier();
;                 *(float4*)(blk + 4 * lane) = *(const float4*)(oq + 4 * lane);
;                 if (lane < 32) *(float4*)(blk + 256 + 4 * lane) = *(const float4*)(oq + 256 + 4 * lane);
;                 if (lane == 0) *(float4*)(blk + 384) = make_float4(ebr[tk - tg], ekr[tk - tg], erk[tk - tg], 0.f);
.LBB0_793:
	v_add_f32_e32 v1, v190, v134
	v_mul_f32_e32 v1, 0xbfb8aa3b, v1
	v_exp_f32_e32 v1, v1
	v_sub_f32_e32 v153, v130, v213
	v_pk_add_f32 v[134:135], v[136:137], v[150:151]
	s_add_i32 s21, s23, 0xfffffc00
	v_add_f32_e32 v1, 1.0, v1
	v_div_scale_f32 v130, s[2:3], v1, v1, 1.0
	v_rcp_f32_e32 v131, v130
	v_div_scale_f32 v136, vcc, 1.0, v1, 1.0
	s_waitcnt vmcnt(1)
	v_sub_f32_e32 v151, v185, v183
	v_fma_f32 v137, -v130, v131, 1.0
	v_fmac_f32_e32 v131, v137, v131
	v_mul_f32_e32 v137, v136, v131
	v_fma_f32 v150, -v130, v137, v136
	v_fmac_f32_e32 v137, v150, v131
	v_fma_f32 v130, -v130, v137, v136
	v_div_fmas_f32 v130, v130, v131, v137
	v_div_fixup_f32 v1, v130, v1, 1.0
	v_mul_f32_e32 v1, 0xbf1b4598, v1
	v_mul_f32_e32 v1, 0x3fb8aa3b, v1
	ds_read2st64_b32 v[130:131], v199 offset0:35 offset1:43
	v_exp_f32_e32 v228, v1
	v_mul_f32_e32 v1, v132, v134
	v_mad_u64_u32 v[136:137], s[2:3], s21, v208, v[176:177]
	v_fma_f32 v229, v152, v228, -v1
	s_waitcnt lgkmcnt(0)
	v_add_f32_e32 v1, v194, v131
	v_mul_f32_e32 v1, 0xbfb8aa3b, v1
	v_exp_f32_e32 v150, v1
	global_load_ushort v165, v[136:137], off
	global_load_ushort v166, v[136:137], off offset:768
	global_load_ushort v1, v[136:137], off offset:1536
	v_mov_b32_e32 v152, v183
	v_fmac_f32_e32 v152, v195, v151
	v_add_f32_e32 v136, 1.0, v150
	v_div_scale_f32 v137, s[2:3], v136, v136, 1.0
	v_rcp_f32_e32 v150, v137
	v_fmac_f32_e32 v213, v191, v153
	v_sub_f32_e32 v131, v184, v182
	v_fma_f32 v131, v196, v131, v182
	v_fma_f32 v151, -v137, v150, 1.0
	v_fmac_f32_e32 v150, v151, v150
	v_div_scale_f32 v151, vcc, 1.0, v136, 1.0
	v_mul_f32_e32 v153, v151, v150
	v_fma_f32 v184, -v137, v153, v151
	v_fmac_f32_e32 v153, v184, v150
	v_fma_f32 v137, -v137, v153, v151
	v_mul_f32_e32 v151, v193, v152
	v_mul_f32_e32 v184, v151, v151
	v_div_fmas_f32 v137, v137, v150, v153
	v_div_fixup_f32 v136, v137, v136, 1.0
	v_mov_b32_dpp v184, v184 quad_perm:[1,0,3,2] row_mask:0xf bank_mask:0xf bound_ctrl:1
	v_fmac_f32_e32 v184, v151, v151
	v_add_f32_e32 v137, -1.0, v136
	v_fma_f32 v137, v192, v137, 1.0
	v_add_f32_dpp v184, v184, v184 quad_perm:[2,3,0,1] row_mask:0xf bank_mask:0xf bound_ctrl:1
	s_mul_hi_u32 s35, s31, 6
	s_mul_i32 s31, s31, 6
	v_add_f32_dpp v184, v184, v184 row_ror:4 row_mask:0xf bank_mask:0xf bound_ctrl:1
	v_mul_f32_e32 v253, v132, v255
	v_mul_f32_e32 v254, v228, v255
	ds_write2st64_b32 v200, v253, v254 offset0:160 offset1:161
	v_mul_f32_e32 v253, v229, v255
	ds_write2st64_b32 v200, v253, v213 offset0:164 offset1:165
	v_cndmask_b32_e64 v255, v254, 1.0, s[98:99]
	v_rcp_f32_e32 v254, v255
	s_nop 0
	v_mul_f32_e32 v253, v155, v254
	v_mul_f32_e32 v254, v154, v254
	ds_write2st64_b32 v200, v253, v254 offset0:162 offset1:163
	v_add_f32_dpp v184, v184, v184 row_ror:8 row_mask:0xf bank_mask:0xf bound_ctrl:1
	v_mov_b32_e32 v185, v184
	s_nop 1
	v_permlane16_swap_b32_e32 v184, v185
	v_add_f32_e32 v184, v184, v185
	v_mov_b32_e32 v185, v184
	s_nop 1
	v_permlane32_swap_b32_e32 v184, v185
	v_add_f32_e32 v184, v184, v185
	v_max_f32_e32 v184, 0x2b8cbccc, v184
	v_rsq_f32_e32 v184, v184
	v_mul_f32_e32 v185, v152, v137
	ds_read_b128 v[228:231], v201
	v_or_b32_e32 v232, s31, v170
	v_mul_f32_e32 v184, v151, v184
	v_mul_f32_e32 v225, v136, v184
	v_mul_f32_e32 v136, v131, v225
	v_lshlrev_b32_e32 v132, 2, v172
	s_nop 0
	v_mov_b32_dpp v136, v136 quad_perm:[1,0,3,2] row_mask:0xf bank_mask:0xf bound_ctrl:1
	v_fmac_f32_e32 v136, v131, v225
	s_nop 1
	v_add_f32_dpp v136, v136, v136 quad_perm:[2,3,0,1] row_mask:0xf bank_mask:0xf bound_ctrl:1
	s_nop 1
	v_add_f32_dpp v136, v136, v136 row_ror:4 row_mask:0xf bank_mask:0xf bound_ctrl:1
	s_nop 1
	v_add_f32_dpp v136, v136, v136 row_ror:8 row_mask:0xf bank_mask:0xf bound_ctrl:1
	v_mov_b32_e32 v137, v136
	s_nop 1
	v_permlane16_swap_b32_e32 v136, v137
	v_add_f32_e32 v150, v136, v137
	v_mul_f32_e32 v136, v131, v185
	v_mov_b32_e32 v152, v150
	s_nop 1
	v_permlane32_swap_b32_e32 v150, v152
	v_mov_b32_dpp v137, v136 quad_perm:[1,0,3,2] row_mask:0xf bank_mask:0xf bound_ctrl:1
	v_fmac_f32_e32 v137, v131, v185
	s_nop 1
	v_add_f32_dpp v137, v137, v137 quad_perm:[2,3,0,1] row_mask:0xf bank_mask:0xf bound_ctrl:1
	s_nop 1
	v_add_f32_dpp v137, v137, v137 row_ror:4 row_mask:0xf bank_mask:0xf bound_ctrl:1
	s_nop 1
	v_add_f32_dpp v137, v137, v137 row_ror:8 row_mask:0xf bank_mask:0xf bound_ctrl:1
	v_mov_b32_e32 v151, v137
	s_nop 1
	v_permlane16_swap_b32_e32 v137, v151
	v_add_f32_e32 v151, v137, v151
	v_mul_f32_e32 v137, v197, v136
	v_mov_b32_e32 v153, v151
	s_nop 1
	v_permlane32_swap_b32_e32 v151, v153
	v_mov_b32_dpp v137, v137 quad_perm:[1,0,3,2] row_mask:0xf bank_mask:0xf bound_ctrl:1
	v_fmac_f32_e32 v137, v197, v136
	s_nop 1
	v_add_f32_dpp v136, v137, v137 quad_perm:[2,3,0,1] row_mask:0xf bank_mask:0xf bound_ctrl:1
	s_nop 1
	v_add_f32_dpp v136, v136, v136 row_ror:4 row_mask:0xf bank_mask:0xf bound_ctrl:1
	s_nop 1
	v_add_f32_dpp v136, v136, v136 row_ror:8 row_mask:0xf bank_mask:0xf bound_ctrl:1
	v_mov_b32_e32 v137, v136
	s_nop 1
	v_permlane16_swap_b32_e32 v136, v137
	v_add_f32_e32 v226, v136, v137
	v_mov_b64_e32 v[136:137], s[18:19]
	v_mad_u64_u32 v[154:155], s[2:3], v232, s25, v[136:137]
	v_mov_b32_e32 v227, v226
	v_mad_u32_u24 v155, s35, v211, v155
	s_nop 0
	v_permlane32_swap_b32_e32 v226, v227
	v_lshl_add_u64 v[136:137], v[154:155], 0, v[132:133]
	s_waitcnt lgkmcnt(0)
	global_store_dwordx4 v[136:137], v[228:231], off
	s_and_saveexec_b64 s[2:3], s[10:11]
	s_cbranch_execz .LBB0_795
	ds_read_b128 v[228:231], v202
	s_waitcnt lgkmcnt(0)
	global_store_dwordx4 v[136:137], v[228:231], off offset:1024

; __device__ __forceinline__ float sigmoidf_(float x) { return 1.f / (1.f + __expf(-x)); }
; __device__ __forceinline__ void p2_rwkv_prep(const Params& P, float* lds) {
;     ...
;                 const float aw = w0c + yt[tk * 64 + cc], aa = a0c + yt[(CT + tk) * 64 + cc];
;                 const float w = __expf(-DECAY_SCALE * sigmoidf_(aw)), a = sigmoidf_(aa);
;                 const float kkv = kraw * kkc;
;                 const float n2 = wave_sum_fast(kkv * kkv);
;                 const float kk = kkv * rsqrtf(fmaxf(n2, 1e-12f));
;                 const float kmod = kraw * (1.f + (a - 1.f) * kac);
;                 const float bb = kk * a;
;                 const float br = wave_sum_fast(bb * r);
;                 ekk[tk - tg] = kk; ew[tk - tg] = w; ebb[tk - tg] = bb; ekm[tk - tg] = kmod; ewr[tk - tg] = w * r - kk * br; ev[tk - tg] = v;
;                 ebr[tk - tg] = br; ekr[tk - tg] = wave_sum_fast(kmod * r); erk[tk - tg] = wave_sum_fast(r * kmod * rkc);
;             }
; #pragma unroll
;             for (int tk = tg; tk < tg + 4; ++tk) {
;                 float* blk = RSB + ((size_t)(tok0 + tk) * RH + h) * RSB_BLK;
;                 float* oq = ot + (tk & 1) * 384;
;                 oq[cc] = ekk[tk - tg]; oq[64 + cc] = ew[tk - tg]; oq[128 + cc] = ebb[tk - tg]; oq[192 + cc] = ekm[tk - tg]; oq[256 + cc] = ewr[tk - tg]; oq[320 + cc] = ev[tk - tg];
;                 __builtin_amdgcn_wave_barrier();
;                 *(float4*)(blk + 4 * lane) = *(const float4*)(oq + 4 * lane);
;                 if (lane < 32) *(float4*)(blk + 256 + 4 * lane) = *(const float4*)(oq + 256 + 4 * lane);
;                 if (lane == 0) *(float4*)(blk + 384) = make_float4(ebr[tk - tg], ekr[tk - tg], erk[tk - tg], 0.f);
.LBB0_797:
	s_or_b64 exec, exec, s[2:3]
	s_nop 0
	v_add_f32_e32 v134, v190, v138
	v_mul_f32_e32 v134, 0xbfb8aa3b, v134
	v_exp_f32_e32 v134, v134
	v_sub_f32_e32 v136, v167, v214
	v_fmac_f32_e32 v214, v191, v136
	v_add_f32_e32 v137, 1.0, v134
	v_div_scale_f32 v138, s[2:3], v137, v137, 1.0
	v_rcp_f32_e32 v154, v138
	v_pk_add_f32 v[134:135], v[142:143], v[144:145]
	v_div_scale_f32 v142, vcc, 1.0, v137, 1.0
	v_fma_f32 v143, -v138, v154, 1.0
	v_fmac_f32_e32 v154, v143, v154
	v_mul_f32_e32 v143, v142, v154
	v_fma_f32 v144, -v138, v143, v142
	v_fmac_f32_e32 v143, v144, v154
	v_fma_f32 v138, -v138, v143, v142
	v_div_fmas_f32 v138, v138, v154, v143
	v_div_fixup_f32 v137, v138, v137, 1.0
	v_mul_f32_e32 v137, 0xbf1b4598, v137
	v_mul_f32_e32 v137, 0x3fb8aa3b, v137
	v_exp_f32_e32 v142, v137
	v_mul_f32_e32 v136, v188, v134
	s_add_i32 s2, s23, 0xfffffbfa
	v_fma_f32 v143, v139, v142, -v136
	v_mul_f32_e32 v253, v188, v255
	v_mul_f32_e32 v254, v142, v255
	ds_write2st64_b32 v203, v253, v254 offset0:166 offset1:167
	v_mul_f32_e32 v253, v143, v255
	ds_write2st64_b32 v203, v253, v214 offset0:170 offset1:171
	v_cndmask_b32_e64 v255, v254, 1.0, s[98:99]
	v_rcp_f32_e32 v254, v255
	s_nop 0
	v_mul_f32_e32 v253, v217, v254
	v_mul_f32_e32 v254, v189, v254
	ds_write2st64_b32 v203, v253, v254 offset0:168 offset1:169
	ds_read_b128 v[142:145], v204
	v_mad_u64_u32 v[136:137], s[2:3], s2, 6, v[170:171]
	v_mov_b64_e32 v[138:139], s[18:19]
	v_mad_u64_u32 v[138:139], s[2:3], v136, s25, v[138:139]
	v_mad_u32_u24 v139, v137, s25, v139
	v_lshl_add_u64 v[136:137], v[138:139], 0, v[132:133]
	s_waitcnt lgkmcnt(0)
	global_store_dwordx4 v[136:137], v[142:145], off
	s_and_saveexec_b64 s[2:3], s[10:11]
	s_cbranch_execz .LBB0_799
	ds_read_b128 v[142:145], v205
	s_waitcnt lgkmcnt(0)
	global_store_dwordx4 v[136:137], v[142:145], off offset:1024

; __device__ __forceinline__ float bf2f(bf16_t b) { return __uint_as_float(((unsigned)b) << 16); }
; __device__ __forceinline__ float sigmoidf_(float x) { return 1.f / (1.f + __expf(-x)); }
; __device__ __forceinline__ void p2_rwkv_prep(const Params& P, float* lds) {
;     ...
;             for (int tk = tg; tk < tg + 4; ++tk) {
;                 const int tok = tok0 + tk;
;                 if (tok >= NTOK) { const float* p = P.state_shift + (size_t)(tok - NTOK) * RCOLS + tid; qr = p[0]; qk = p[RW]; qv = p[2 * RW]; }
;                 const float cr = nr[tk & 3], ck = nk[tk & 3], cv = nv[tk & 3];
;                 if (tk + 4 < CT) { const bf16_t* p = prw + (size_t)(tok + 4) * RCOLS + tid; nr[tk & 3] = bf2f(p[0]); nk[tk & 3] = bf2f(p[RW]); nv[tk & 3] = bf2f(p[2 * RW]); }
;                 const float r = cr + (qr - cr) * mur, kraw = ck + (qk - ck) * muk, v = cv + (qv - cv) * muv;
;                 qr = cr; qk = ck; qv = cv;
;                 const float aw = w0c + yt[tk * 64 + cc], aa = a0c + yt[(CT + tk) * 64 + cc];
;                 const float w = __expf(-DECAY_SCALE * sigmoidf_(aw)), a = sigmoidf_(aa);
;                 const float kkv = kraw * kkc;
;                 const float n2 = wave_sum_fast(kkv * kkv);
;                 const float kk = kkv * rsqrtf(fmaxf(n2, 1e-12f));
;                 const float kmod = kraw * (1.f + (a - 1.f) * kac);
;                 const float bb = kk * a;
;                 const float br = wave_sum_fast(bb * r);
;                 ekk[tk - tg] = kk; ew[tk - tg] = w; ebb[tk - tg] = bb; ekm[tk - tg] = kmod; ewr[tk - tg] = w * r - kk * br; ev[tk - tg] = v;
;                 ebr[tk - tg] = br; ekr[tk - tg] = wave_sum_fast(kmod * r); erk[tk - tg] = wave_sum_fast(r * kmod * rkc);
.LBB0_809:
	s_or_b64 exec, exec, s[2:3]
	s_cmpk_lt_i32 s16, 0x4000
	s_cbranch_scc1 .LBB0_811
	s_add_i32 s2, s23, 0xffffbbfd
	v_mad_u64_u32 v[130:131], s[2:3], s2, v210, v[178:179]
	global_load_dword v182, v[130:131], off
	global_load_dword v183, v[130:131], off offset:1536
	global_load_dword v215, v[130:131], off offset:3072
.LBB0_811:
	ds_read2st64_b32 v[134:135], v199 offset0:36 offset1:44
	v_lshlrev_b32_e32 v188, 16, v156
	s_waitcnt vmcnt(2)
	v_sub_f32_e32 v131, v182, v188
	v_fma_f32 v152, v196, v131, v188
	v_lshlrev_b32_e32 v189, 16, v158
	s_waitcnt lgkmcnt(0)
	v_add_f32_e32 v130, v194, v135
	v_mul_f32_e32 v130, 0xbfb8aa3b, v130
	v_exp_f32_e32 v130, v130
	s_waitcnt vmcnt(1)
	v_sub_f32_e32 v135, v183, v189
	v_fma_f32 v135, v195, v135, v189
	v_lshlrev_b32_e32 v213, 16, v157
	v_add_f32_e32 v130, 1.0, v130
	v_div_scale_f32 v131, s[2:3], v130, v130, 1.0
	v_rcp_f32_e32 v136, v131
	v_div_scale_f32 v137, vcc, 1.0, v130, 1.0
	s_cmpk_lt_i32 s17, 0x4000
	v_fma_f32 v138, -v131, v136, 1.0
	v_fmac_f32_e32 v136, v138, v136
	v_mul_f32_e32 v138, v137, v136
	v_fma_f32 v139, -v131, v138, v137
	v_fmac_f32_e32 v138, v139, v136
	v_fma_f32 v131, -v131, v138, v137
	v_mul_f32_e32 v137, v193, v135
	v_mul_f32_e32 v139, v137, v137
	v_div_fmas_f32 v131, v131, v136, v138
	v_div_fixup_f32 v130, v131, v130, 1.0
	v_mov_b32_dpp v139, v139 quad_perm:[1,0,3,2] row_mask:0xf bank_mask:0xf bound_ctrl:1
	v_fmac_f32_e32 v139, v137, v137
	v_add_f32_e32 v131, -1.0, v130
	v_fma_f32 v131, v192, v131, 1.0
	v_add_f32_dpp v139, v139, v139 quad_perm:[2,3,0,1] row_mask:0xf bank_mask:0xf bound_ctrl:1
	v_mul_f32_e32 v155, v135, v131
	v_mov_b32_e32 v157, v213
	v_add_f32_dpp v139, v139, v139 row_ror:4 row_mask:0xf bank_mask:0xf bound_ctrl:1
	v_mov_b32_e32 v138, v188
	s_nop 0
	v_add_f32_dpp v139, v139, v139 row_ror:8 row_mask:0xf bank_mask:0xf bound_ctrl:1
	v_mov_b32_e32 v140, v139
	s_nop 1
	v_permlane16_swap_b32_e32 v139, v140
	v_add_f32_e32 v139, v139, v140
	v_mov_b32_e32 v140, v139
	s_nop 1
	v_permlane32_swap_b32_e32 v139, v140
	v_add_f32_e32 v139, v139, v140
	v_max_f32_e32 v139, 0x2b8cbccc, v139
	v_rsq_f32_e32 v139, v139
	s_nop 0
	v_mul_f32_e32 v154, v137, v139
	v_mul_f32_e32 v156, v130, v154
	v_mul_f32_e32 v130, v152, v156
	s_nop 1
	v_mov_b32_dpp v130, v130 quad_perm:[1,0,3,2] row_mask:0xf bank_mask:0xf bound_ctrl:1
	v_fmac_f32_e32 v130, v152, v156
	s_nop 1
	v_add_f32_dpp v130, v130, v130 quad_perm:[2,3,0,1] row_mask:0xf bank_mask:0xf bound_ctrl:1
	s_nop 1
	v_add_f32_dpp v130, v130, v130 row_ror:4 row_mask:0xf bank_mask:0xf bound_ctrl:1
	s_nop 1
	v_add_f32_dpp v130, v130, v130 row_ror:8 row_mask:0xf bank_mask:0xf bound_ctrl:1
	v_mov_b32_e32 v131, v130
	s_nop 1
	v_permlane16_swap_b32_e32 v130, v131
	v_add_f32_e32 v136, v130, v131
	v_mul_f32_e32 v130, v152, v155
	v_mov_b32_e32 v148, v136
	s_nop 1
	v_permlane32_swap_b32_e32 v136, v148
	v_mov_b32_dpp v131, v130 quad_perm:[1,0,3,2] row_mask:0xf bank_mask:0xf bound_ctrl:1
	v_fmac_f32_e32 v131, v152, v155
	s_nop 1
	v_add_f32_dpp v131, v131, v131 quad_perm:[2,3,0,1] row_mask:0xf bank_mask:0xf bound_ctrl:1
	s_nop 1
	v_add_f32_dpp v131, v131, v131 row_ror:4 row_mask:0xf bank_mask:0xf bound_ctrl:1
	s_nop 1
	v_add_f32_dpp v131, v131, v131 row_ror:8 row_mask:0xf bank_mask:0xf bound_ctrl:1
	v_mov_b32_e32 v135, v131
	s_nop 1
	v_permlane16_swap_b32_e32 v131, v135
	v_add_f32_e32 v137, v131, v135
	v_mul_f32_e32 v131, v197, v130
	v_mov_b32_e32 v149, v137
	s_nop 1
	v_permlane32_swap_b32_e32 v137, v149
	v_mov_b32_dpp v131, v131 quad_perm:[1,0,3,2] row_mask:0xf bank_mask:0xf bound_ctrl:1
	v_fmac_f32_e32 v131, v197, v130
	v_mov_b32_e32 v135, v189
	s_nop 0
	v_add_f32_dpp v130, v131, v131 quad_perm:[2,3,0,1] row_mask:0xf bank_mask:0xf bound_ctrl:1
	s_nop 1
	v_add_f32_dpp v130, v130, v130 row_ror:4 row_mask:0xf bank_mask:0xf bound_ctrl:1
	s_nop 1
	v_add_f32_dpp v130, v130, v130 row_ror:8 row_mask:0xf bank_mask:0xf bound_ctrl:1
	v_mov_b32_e32 v131, v130
	s_nop 1
	v_permlane16_swap_b32_e32 v130, v131
	v_add_f32_e32 v158, v130, v131
	v_mov_b32_e32 v167, v158
	s_nop 1
	v_permlane32_swap_b32_e32 v158, v167
	s_cbranch_scc1 .LBB0_813
	s_add_i32 s2, s23, 0xffffbbfe
	v_mad_u64_u32 v[130:131], s[2:3], s2, v210, v[178:179]
	global_load_dword v138, v[130:131], off
	global_load_dword v135, v[130:131], off offset:1536
	global_load_dword v157, v[130:131], off offset:3072
; __device__ __forceinline__ float bf2f(bf16_t b) { return __uint_as_float(((unsigned)b) << 16); }
; __device__ __forceinline__ float sigmoidf_(float x) { return 1.f / (1.f + __expf(-x)); }
; __device__ __forceinline__ void p2_rwkv_prep(const Params& P, float* lds) {
;     ...
;             for (int tk = tg; tk < tg + 4; ++tk) {
;                 const int tok = tok0 + tk;
;                 if (tok >= NTOK) { const float* p = P.state_shift + (size_t)(tok - NTOK) * RCOLS + tid; qr = p[0]; qk = p[RW]; qv = p[2 * RW]; }
;                 const float cr = nr[tk & 3], ck = nk[tk & 3], cv = nv[tk & 3];
;                 if (tk + 4 < CT) { const bf16_t* p = prw + (size_t)(tok + 4) * RCOLS + tid; nr[tk & 3] = bf2f(p[0]); nk[tk & 3] = bf2f(p[RW]); nv[tk & 3] = bf2f(p[2 * RW]); }
;                 const float r = cr + (qr - cr) * mur, kraw = ck + (qk - ck) * muk, v = cv + (qv - cv) * muv;
;                 qr = cr; qk = ck; qv = cv;
;                 const float aw = w0c + yt[tk * 64 + cc], aa = a0c + yt[(CT + tk) * 64 + cc];
;                 const float w = __expf(-DECAY_SCALE * sigmoidf_(aw)), a = sigmoidf_(aa);
;                 const float kkv = kraw * kkc;
;                 const float n2 = wave_sum_fast(kkv * kkv);
;                 const float kk = kkv * rsqrtf(fmaxf(n2, 1e-12f));
;                 const float kmod = kraw * (1.f + (a - 1.f) * kac);
;                 const float bb = kk * a;
;                 const float br = wave_sum_fast(bb * r);
;                 ekk[tk - tg] = kk; ew[tk - tg] = w; ebb[tk - tg] = bb; ekm[tk - tg] = kmod; ewr[tk - tg] = w * r - kk * br; ev[tk - tg] = v;
;                 ebr[tk - tg] = br; ekr[tk - tg] = wave_sum_fast(kmod * r); erk[tk - tg] = wave_sum_fast(r * kmod * rkc);
.LBB0_813:
	ds_read2st64_b32 v[130:131], v199 offset0:37 offset1:45
	v_lshlrev_b32_e32 v186, 16, v159
	v_lshlrev_b32_e32 v187, 16, v161
	s_waitcnt vmcnt(1)
	v_sub_f32_e32 v135, v135, v187
	v_fma_f32 v135, v195, v135, v187
	s_waitcnt lgkmcnt(0)
	v_add_f32_e32 v131, v194, v131
	v_mul_f32_e32 v131, 0xbfb8aa3b, v131
	v_exp_f32_e32 v139, v131
	v_sub_f32_e32 v131, v138, v186
	v_fma_f32 v131, v196, v131, v186
	v_lshlrev_b32_e32 v214, 16, v160
	v_add_f32_e32 v138, 1.0, v139
	v_div_scale_f32 v139, s[2:3], v138, v138, 1.0
	v_rcp_f32_e32 v140, v139
	v_div_scale_f32 v141, vcc, 1.0, v138, 1.0
	s_cmpk_lt_i32 s20, 0x4000
	v_fma_f32 v142, -v139, v140, 1.0
	v_fmac_f32_e32 v140, v142, v140
	v_mul_f32_e32 v142, v141, v140
	v_fma_f32 v143, -v139, v142, v141
	v_fmac_f32_e32 v142, v143, v140
	v_fma_f32 v139, -v139, v142, v141
	v_mul_f32_e32 v141, v193, v135
	v_mul_f32_e32 v143, v141, v141
	v_div_fmas_f32 v139, v139, v140, v142
	v_div_fixup_f32 v138, v139, v138, 1.0
	v_mov_b32_dpp v143, v143 quad_perm:[1,0,3,2] row_mask:0xf bank_mask:0xf bound_ctrl:1
	v_fmac_f32_e32 v143, v141, v141
	v_add_f32_e32 v139, -1.0, v138
	v_fma_f32 v139, v192, v139, 1.0
	v_add_f32_dpp v143, v143, v143 quad_perm:[2,3,0,1] row_mask:0xf bank_mask:0xf bound_ctrl:1
	v_mul_f32_e32 v160, v135, v139
	v_mov_b32_e32 v168, v214
	v_add_f32_dpp v143, v143, v143 row_ror:4 row_mask:0xf bank_mask:0xf bound_ctrl:1
	s_nop 1
	v_add_f32_dpp v143, v143, v143 row_ror:8 row_mask:0xf bank_mask:0xf bound_ctrl:1
	v_mov_b32_e32 v144, v143
	s_nop 1
	v_permlane16_swap_b32_e32 v143, v144
	v_add_f32_e32 v143, v143, v144
	v_mov_b32_e32 v144, v143
	s_nop 1
	v_permlane32_swap_b32_e32 v143, v144
	v_add_f32_e32 v143, v143, v144
	v_max_f32_e32 v143, 0x2b8cbccc, v143
	v_rsq_f32_e32 v143, v143
	v_mov_b32_e32 v144, v186
	v_mul_f32_e32 v159, v141, v143
	v_mul_f32_e32 v161, v138, v159
	v_mul_f32_e32 v135, v131, v161
	s_nop 1
	v_mov_b32_dpp v135, v135 quad_perm:[1,0,3,2] row_mask:0xf bank_mask:0xf bound_ctrl:1
	v_fmac_f32_e32 v135, v131, v161
	s_nop 1
	v_add_f32_dpp v135, v135, v135 quad_perm:[2,3,0,1] row_mask:0xf bank_mask:0xf bound_ctrl:1
	s_nop 1
	v_add_f32_dpp v135, v135, v135 row_ror:4 row_mask:0xf bank_mask:0xf bound_ctrl:1
	s_nop 1
	v_add_f32_dpp v135, v135, v135 row_ror:8 row_mask:0xf bank_mask:0xf bound_ctrl:1
	v_mov_b32_e32 v138, v135
	s_nop 1
	v_permlane16_swap_b32_e32 v135, v138
	v_add_f32_e32 v138, v135, v138
	v_mul_f32_e32 v135, v131, v160
	v_mul_f32_e32 v142, v197, v135
	v_mov_b32_e32 v140, v138
	v_mov_b32_dpp v139, v135 quad_perm:[1,0,3,2] row_mask:0xf bank_mask:0xf bound_ctrl:1
	v_mov_b32_dpp v142, v142 quad_perm:[1,0,3,2] row_mask:0xf bank_mask:0xf bound_ctrl:1
	v_fmac_f32_e32 v139, v131, v160
	v_fmac_f32_e32 v142, v197, v135
	v_permlane32_swap_b32_e32 v138, v140
	v_add_f32_dpp v139, v139, v139 quad_perm:[2,3,0,1] row_mask:0xf bank_mask:0xf bound_ctrl:1
	v_add_f32_dpp v135, v142, v142 quad_perm:[2,3,0,1] row_mask:0xf bank_mask:0xf bound_ctrl:1
	s_nop 0
	v_add_f32_dpp v139, v139, v139 row_ror:4 row_mask:0xf bank_mask:0xf bound_ctrl:1
	v_add_f32_dpp v135, v135, v135 row_ror:4 row_mask:0xf bank_mask:0xf bound_ctrl:1
	s_nop 0
	v_add_f32_dpp v139, v139, v139 row_ror:8 row_mask:0xf bank_mask:0xf bound_ctrl:1
	v_add_f32_dpp v135, v135, v135 row_ror:8 row_mask:0xf bank_mask:0xf bound_ctrl:1
	v_mov_b32_e32 v141, v139
	v_mov_b32_e32 v142, v135
	s_nop 0
	v_permlane16_swap_b32_e32 v139, v141
	v_permlane16_swap_b32_e32 v135, v142
	v_add_f32_e32 v139, v139, v141
	v_add_f32_e32 v169, v135, v142
	v_mov_b32_e32 v141, v139
	v_mov_b32_e32 v217, v169
	s_nop 0
	v_permlane32_swap_b32_e32 v139, v141
	v_permlane32_swap_b32_e32 v169, v217
	v_mov_b32_e32 v135, v187
	s_cbranch_scc1 .LBB0_815
	s_add_i32 s2, s23, 0xffffbbff
	v_mad_u64_u32 v[142:143], s[2:3], s2, v210, v[178:179]
	global_load_dword v144, v[142:143], off
	global_load_dword v135, v[142:143], off offset:1536
	global_load_dword v168, v[142:143], off offset:3072
; __device__ __forceinline__ float bf2f(bf16_t b) { return __uint_as_float(((unsigned)b) << 16); }
; __device__ __forceinline__ float sigmoidf_(float x) { return 1.f / (1.f + __expf(-x)); }
; __device__ __forceinline__ void p2_rwkv_prep(const Params& P, float* lds) {
;     ...
;             for (int tk = tg; tk < tg + 4; ++tk) {
;                 const int tok = tok0 + tk;
;                 if (tok >= NTOK) { const float* p = P.state_shift + (size_t)(tok - NTOK) * RCOLS + tid; qr = p[0]; qk = p[RW]; qv = p[2 * RW]; }
;                 const float cr = nr[tk & 3], ck = nk[tk & 3], cv = nv[tk & 3];
;                 if (tk + 4 < CT) { const bf16_t* p = prw + (size_t)(tok + 4) * RCOLS + tid; nr[tk & 3] = bf2f(p[0]); nk[tk & 3] = bf2f(p[RW]); nv[tk & 3] = bf2f(p[2 * RW]); }
;                 const float r = cr + (qr - cr) * mur, kraw = ck + (qk - ck) * muk, v = cv + (qv - cv) * muv;
;                 qr = cr; qk = ck; qv = cv;
;                 const float aw = w0c + yt[tk * 64 + cc], aa = a0c + yt[(CT + tk) * 64 + cc];
;                 const float w = __expf(-DECAY_SCALE * sigmoidf_(aw)), a = sigmoidf_(aa);
;                 const float kkv = kraw * kkc;
;                 const float n2 = wave_sum_fast(kkv * kkv);
;                 const float kk = kkv * rsqrtf(fmaxf(n2, 1e-12f));
;                 const float kmod = kraw * (1.f + (a - 1.f) * kac);
;                 const float bb = kk * a;
;                 const float br = wave_sum_fast(bb * r);
;                 ekk[tk - tg] = kk; ew[tk - tg] = w; ebb[tk - tg] = bb; ekm[tk - tg] = kmod; ewr[tk - tg] = w * r - kk * br; ev[tk - tg] = v;
;                 ebr[tk - tg] = br; ekr[tk - tg] = wave_sum_fast(kmod * r); erk[tk - tg] = wave_sum_fast(r * kmod * rkc);
.LBB0_815:
	ds_read2st64_b32 v[142:143], v199 offset0:38 offset1:46
	v_lshlrev_b32_e32 v184, 16, v162
	v_lshlrev_b32_e32 v185, 16, v164
	s_waitcnt vmcnt(1)
	v_sub_f32_e32 v135, v135, v185
	v_fma_f32 v135, v195, v135, v185
	s_waitcnt lgkmcnt(0)
	v_add_f32_e32 v143, v194, v143
	v_mul_f32_e32 v143, 0xbfb8aa3b, v143
	v_exp_f32_e32 v145, v143
	v_sub_f32_e32 v143, v144, v184
	v_lshlrev_b32_e32 v216, 16, v163
	v_fma_f32 v143, v196, v143, v184
	v_add_f32_e32 v144, 1.0, v145
	v_div_scale_f32 v145, s[2:3], v144, v144, 1.0
	v_rcp_f32_e32 v146, v145
	v_div_scale_f32 v147, vcc, 1.0, v144, 1.0
	s_cmpk_lt_i32 s21, 0x4000
	v_fma_f32 v150, -v145, v146, 1.0
	v_fmac_f32_e32 v146, v150, v146
	v_mul_f32_e32 v150, v147, v146
	v_fma_f32 v151, -v145, v150, v147
	v_fmac_f32_e32 v150, v151, v146
	v_fma_f32 v145, -v145, v150, v147
	v_mul_f32_e32 v147, v193, v135
	v_mul_f32_e32 v151, v147, v147
	v_div_fmas_f32 v145, v145, v146, v150
	v_div_fixup_f32 v144, v145, v144, 1.0
	v_mov_b32_dpp v151, v151 quad_perm:[1,0,3,2] row_mask:0xf bank_mask:0xf bound_ctrl:1
	v_fmac_f32_e32 v151, v147, v147
	v_add_f32_e32 v145, -1.0, v144
	v_fma_f32 v145, v192, v145, 1.0
	v_add_f32_dpp v151, v151, v151 quad_perm:[2,3,0,1] row_mask:0xf bank_mask:0xf bound_ctrl:1
	v_mul_f32_e32 v164, v135, v145
	v_mov_b32_e32 v162, v216
	v_add_f32_dpp v151, v151, v151 row_ror:4 row_mask:0xf bank_mask:0xf bound_ctrl:1
	v_mov_b32_e32 v221, v184
	s_nop 0
	v_add_f32_dpp v151, v151, v151 row_ror:8 row_mask:0xf bank_mask:0xf bound_ctrl:1
	v_mov_b32_e32 v153, v151
	s_nop 1
	v_permlane16_swap_b32_e32 v151, v153
	v_add_f32_e32 v151, v151, v153
	v_mov_b32_e32 v153, v151
	s_nop 1
	v_permlane32_swap_b32_e32 v151, v153
	v_add_f32_e32 v151, v151, v153
	v_max_f32_e32 v151, 0x2b8cbccc, v151
	v_rsq_f32_e32 v151, v151
	v_mov_b32_e32 v153, v185
	v_mul_f32_e32 v163, v147, v151
	v_mul_f32_e32 v218, v144, v163
	v_mul_f32_e32 v135, v143, v218
	s_nop 1
	v_mov_b32_dpp v135, v135 quad_perm:[1,0,3,2] row_mask:0xf bank_mask:0xf bound_ctrl:1
	v_fmac_f32_e32 v135, v143, v218
	s_nop 1
	v_add_f32_dpp v135, v135, v135 quad_perm:[2,3,0,1] row_mask:0xf bank_mask:0xf bound_ctrl:1
	s_nop 1
	v_add_f32_dpp v135, v135, v135 row_ror:4 row_mask:0xf bank_mask:0xf bound_ctrl:1
	s_nop 1
	v_add_f32_dpp v135, v135, v135 row_ror:8 row_mask:0xf bank_mask:0xf bound_ctrl:1
	v_mov_b32_e32 v144, v135
	s_nop 1
	v_permlane16_swap_b32_e32 v135, v144
	v_add_f32_e32 v144, v135, v144
	v_mul_f32_e32 v135, v143, v164
	v_mul_f32_e32 v150, v197, v135
	v_mov_b32_e32 v146, v144
	v_mov_b32_dpp v145, v135 quad_perm:[1,0,3,2] row_mask:0xf bank_mask:0xf bound_ctrl:1
	v_mov_b32_dpp v150, v150 quad_perm:[1,0,3,2] row_mask:0xf bank_mask:0xf bound_ctrl:1
	v_fmac_f32_e32 v145, v143, v164
	v_fmac_f32_e32 v150, v197, v135
	v_permlane32_swap_b32_e32 v144, v146
	v_add_f32_dpp v145, v145, v145 quad_perm:[2,3,0,1] row_mask:0xf bank_mask:0xf bound_ctrl:1
	v_add_f32_dpp v135, v150, v150 quad_perm:[2,3,0,1] row_mask:0xf bank_mask:0xf bound_ctrl:1
	s_nop 0
	v_add_f32_dpp v145, v145, v145 row_ror:4 row_mask:0xf bank_mask:0xf bound_ctrl:1
	v_add_f32_dpp v135, v135, v135 row_ror:4 row_mask:0xf bank_mask:0xf bound_ctrl:1
	s_nop 0
	v_add_f32_dpp v145, v145, v145 row_ror:8 row_mask:0xf bank_mask:0xf bound_ctrl:1
	v_add_f32_dpp v135, v135, v135 row_ror:8 row_mask:0xf bank_mask:0xf bound_ctrl:1
	v_mov_b32_e32 v147, v145
	v_mov_b32_e32 v150, v135
	s_nop 0
	v_permlane16_swap_b32_e32 v145, v147
	v_permlane16_swap_b32_e32 v135, v150
	v_add_f32_e32 v145, v145, v147
	v_add_f32_e32 v219, v135, v150
	v_mov_b32_e32 v147, v145
	v_mov_b32_e32 v220, v219
	s_nop 0
	v_permlane32_swap_b32_e32 v145, v147
	v_permlane32_swap_b32_e32 v219, v220
	s_cbranch_scc1 .LBB0_817
	s_add_i32 s2, s23, 0xffffbc00
	v_mad_u64_u32 v[150:151], s[2:3], s2, v210, v[178:179]
	global_load_dword v221, v[150:151], off
	global_load_dword v153, v[150:151], off offset:1536
	global_load_dword v162, v[150:151], off offset:3072

; __device__ __forceinline__ float bf2f(bf16_t b) { return __uint_as_float(((unsigned)b) << 16); }
; __device__ __forceinline__ void prep_produce(const Params& P, const bf16_t* __restrict__ prw, int ch, float* buf, int j, float mux) {
;     constexpr int CT = 8;
;     const int tok0 = ch * CT;
;     float pv = 0.f;
;     if (tok0 < NTOK && (tok0 & (SEQ - 1))) pv = bf2f(prw[(size_t)(tok0 - 1) * RCOLS + 1152 + j]);
; __device__ __forceinline__ void p2_rwkv_prep(const Params& P, float* lds) {
;     ...
;         if (tid >= RW) { if (ch + NPREP < NCHK) prep_produce(P, prw, ch + NPREP, bufn, tid - RW, mux); }
.LBB0_834:
	s_andn2_saveexec_b64 s[0:1], s[0:1]
	s_cbranch_execz .LBB0_763
	s_cmpk_gt_i32 s30, 0x783
	s_cbranch_scc1 .LBB0_763
	s_add_i32 s16, s30, 0x80
	s_cmpk_gt_i32 s30, 0x77f
	s_cselect_b64 s[2:3], -1, 0
	s_and_b32 s16, s16, 0x1ff
	s_cmp_eq_u32 s16, 0
	s_cselect_b64 s[16:17], -1, 0
	s_or_b64 s[16:17], s[2:3], s[16:17]
	v_mov_b32_e32 v130, 0
	s_and_b64 vcc, exec, s[16:17]
	s_cbranch_vccnz .LBB0_838
	s_add_i32 s16, s23, -8
	v_mad_i64_i32 v[130:131], s[16:17], s16, v208, v[180:181]
	global_load_ushort v1, v[130:131], off offset:2304
	s_waitcnt vmcnt(0)
	v_lshlrev_b32_e32 v130, 16, v1

; #define LAS __attribute__((address_space(3)))
; __device__ __forceinline__ void p3_scan_and_sb(const Params& P, float* lds) {
;     ...
;     } else {
;         const int grp = wave >> 2, gw = wave & 3;
;         volatile LAS unsigned* gctl = (volatile LAS unsigned*)((LAS unsigned char*)lds + LDS_CTL + 32);
;         if (tid < 8) gctl[tid] = 0u;
;         __syncthreads();
;         sba::Grp4 G; G.ctr = gctl + grp; G.gen = 0u;
;         if (grp == 1) sb_decode_wave_loop(P, lds);
.LBB0_939:
	s_cmp_lt_i32 s60, 4
	s_cselect_b64 s[0:1], -1, 0
	s_cmp_gt_i32 s61, 3
	s_cselect_b64 s[2:3], -1, 0
	s_and_b64 s[34:35], s[0:1], s[2:3]
	s_andn2_b64 vcc, exec, s[34:35]
	s_cbranch_vccnz .LBB0_1576
	v_writelane_b32 v252, s34, 54
	s_cmpk_lt_u32 s56, 0x60
	v_and_b32_e32 v1, 63, v0
	v_writelane_b32 v252, s35, 55
	v_writelane_b32 v252, s80, 56
	s_cselect_b64 s[52:53], -1, 0
	s_cmpk_gt_u32 s56, 0x5f
	v_writelane_b32 v252, s81, 57
	v_writelane_b32 v252, s56, 53
	v_writelane_b32 v252, s60, 51
	s_mov_b64 s[0:1], -1
	s_waitcnt vmcnt(0)
	v_writelane_b32 v252, s61, 52
	s_barrier
	v_writelane_b32 v252, s57, 50
	s_cbranch_scc0 .LBB0_1203
	v_writelane_b32 v252, s52, 58
	v_cmp_gt_u32_e32 vcc, 8, v0
	s_nop 0
	v_writelane_b32 v252, s53, 59
	s_and_saveexec_b64 s[0:1], vcc
	v_lshl_add_u32 v2, v0, 2, 0
	v_add_u32_e32 v2, 0x26020, v2
	v_mov_b32_e32 v3, 0
	ds_write_b32 v2, v3
	s_or_b64 exec, exec, s[0:1]
	v_lshrrev_b32_e32 v94, 8, v0
	s_waitcnt lgkmcnt(0)
	s_barrier
	v_cmp_eq_u32_e32 vcc, 1, v94
	s_mov_b64 s[0:1], exec
	v_writelane_b32 v252, s0, 60
	s_nop 1
	v_writelane_b32 v252, s1, 61
	s_cmpk_gt_u32 s56, 0x7f
	s_cselect_b64 s[2:3], exec, 0
	s_or_b64 vcc, vcc, s[2:3]
	s_and_b64 s[0:1], s[0:1], vcc
	s_mov_b64 exec, s[0:1]
	s_cbranch_execz .LBB0_1092
	v_readfirstlane_b32 s2, v94
	s_cmp_eq_u32 s2, 0
	s_cselect_b32 s100, 1, 0x7fffffff
	s_add_u32 s0, s78, 0x3900
	s_addc_u32 s1, s79, 0
	v_writelane_b32 v252, s0, 62
	v_mov_b32_e32 v95, 0
	v_cmp_eq_u32_e64 s[4:5], 0, v1
	v_writelane_b32 v252, s1, 63
	s_and_saveexec_b64 s[0:1], s[4:5]
	v_readlane_b32 s22, v252, 48
	v_readlane_b32 s23, v252, 49
	s_cbranch_execz .LBB0_948
	s_mov_b64 s[6:7], exec
	v_mbcnt_lo_u32_b32 v2, s6, 0
	v_mbcnt_hi_u32_b32 v2, s7, v2
	v_cmp_eq_u32_e32 vcc, 0, v2
	s_and_saveexec_b64 s[2:3], vcc
	s_cbranch_execz .LBB0_947
	s_bcnt1_i32_b64 s6, s[6:7]
	s_lshl_b32 s6, s6, 1
	v_mov_b32_e32 v4, s6
	v_readlane_b32 s6, v252, 62
	v_mov_b32_e32 v3, 0
	v_readlane_b32 s7, v252, 63
	s_nop 4
	global_atomic_add v3, v3, v4, s[6:7] sc0

; #define LAS __attribute__((address_space(3)))
; __device__ __forceinline__ unsigned xb_ld(unsigned* p)              { return __hip_atomic_load(p, __ATOMIC_RELAXED, __HIP_MEMORY_SCOPE_AGENT); }
; #define XB_SPIN(cond, bar) do { unsigned _sp = 0; while (cond) { __builtin_amdgcn_s_sleep(1); \
;     if ((++_sp & 255u) == 0u) { if (xb_ld(&(bar)[XB_TMO])) break; if (_sp > XB_SPIN_CAP) { atomicAdd(&(bar)[XB_TMO], 1u); break; } } } } while (0)
; __device__ __forceinline__ void p3_scan_and_sb(const Params& P, float* lds) {
;     ...
;     if (blockIdx.x < 96) {
;         const int bh = blockIdx.x >> 2, quarter = blockIdx.x & 3, b = bh / RH, h = bh % RH;
;         volatile LAS unsigned* scw = (volatile LAS unsigned*)((LAS unsigned char*)lds + SC_CTL_OFF);
;         if (tid < 5) scw[tid] = 0u;
;         if (tid == 0) { XB_SPIN(xb_ld(ctl + QW_PREP_W) < (unsigned)NPREP, ctl); __builtin_amdgcn_fence(__ATOMIC_ACQUIRE, "agent"); asm volatile("s_waitcnt vmcnt(0)" ::: "memory"); }
;         __syncthreads();
.LBB0_1203:
	s_and_b64 vcc, exec, s[0:1]
	s_cbranch_vccz .LBB0_1261
	v_cmp_gt_u32_e32 vcc, 5, v0
	s_and_saveexec_b64 s[0:1], vcc
	v_lshl_add_u32 v2, v0, 2, 0
	v_add_u32_e32 v2, 0x23000, v2
	v_mov_b32_e32 v3, 0
	ds_write_b32 v2, v3
	s_or_b64 exec, exec, s[0:1]
	s_and_saveexec_b64 s[0:1], s[80:81]
	s_cbranch_execz .LBB0_1221
	v_mov_b32_e32 v2, 0x3000
	global_load_dword v2, v2, s[78:79] offset:3328 sc1
	s_movk_i32 s10, 0x7f
	s_add_u32 s2, s78, 0x3d00
	s_addc_u32 s3, s79, 0
	s_waitcnt vmcnt(0)
	v_cmp_lt_u32_e32 vcc, s10, v2
	s_cbranch_vccnz .LBB0_1220
	s_mov_b32 s11, 1
	v_mov_b32_e32 v2, 0
	s_branch .LBB0_1210

; __device__ __forceinline__ unsigned xb_ld(unsigned* p)              { return __hip_atomic_load(p, __ATOMIC_RELAXED, __HIP_MEMORY_SCOPE_AGENT); }
; #define XB_SPIN(cond, bar) do { unsigned _sp = 0; while (cond) { __builtin_amdgcn_s_sleep(1); \
;     if ((++_sp & 255u) == 0u) { if (xb_ld(&(bar)[XB_TMO])) break; if (_sp > XB_SPIN_CAP) { atomicAdd(&(bar)[XB_TMO], 1u); break; } } } } while (0)
; __device__ __forceinline__ void p3_scan_and_sb(const Params& P, float* lds) {
;     ...
;     sb_decode_wave_loop(P, lds);
;     if (lane == 0) XB_SPIN(xb_ld(ctl + QW_PREP_W) < (unsigned)NPREP, ctl);
;     __builtin_amdgcn_fence(__ATOMIC_ACQUIRE, "agent");
.LBB0_1555:
	s_and_saveexec_b64 s[0:1], s[4:5]
	v_readlane_b32 s58, v252, 48
	v_readlane_b32 s59, v252, 49
	s_load_dwordx8 s[68:75], s[58:59], 0xc0
	v_readlane_b32 s80, v252, 56
	v_readlane_b32 s60, v252, 51
	v_readlane_b32 s34, v252, 54
	v_readlane_b32 s81, v252, 57
	v_readlane_b32 s56, v252, 53
	v_readlane_b32 s61, v252, 52
	v_readlane_b32 s57, v252, 50
	v_readlane_b32 s35, v252, 55
	s_cbranch_execz .LBB0_1568
	v_mov_b32_e32 v1, 0x3000
	global_load_dword v1, v1, s[78:79] offset:3328 sc1
	s_movk_i32 s10, 0x7f
	s_add_u32 s2, s78, 0x3d00
	s_addc_u32 s3, s79, 0
	s_waitcnt vmcnt(0)
	v_cmp_lt_u32_e32 vcc, s10, v1
	s_cbranch_vccnz .LBB0_1568
	s_mov_b32 s11, 1
	v_mov_b32_e32 v1, 0
	s_branch .LBB0_1559
